# final rmsnorm pass: final_g hoisted out of the row loop, all four z row-quarters prefetched at once, in-row vmcnt waits removed
# speedup vs baseline: 1.0407x; 1.0014x over previous
; __global__ void __launch_bounds__(NWAVES * 64, 2) mixer_fwd(Args args) {
;     ...
;         const int gw = vcu * NWAVES + wave, NGW = G * NWAVES; const f32x4* fg = (const f32x4*)args.in[12] + 2 * lane;
;         const bf16* zb = (const bf16*)(ws + WS_QKVB);
;         for (int m = gw; m < MTOK; m += NGW) {
;             const float s = wave_sum(lane < 32 ? part[(size_t)m * 32 + lane] : 0.f);
;             const float r = 1.f / sqrtf(s * (1.f / DM) + 1e-6f);
;             const v4u* zr = (const v4u*)(zb + (size_t)m * DM) + lane; f32x4* orow = (f32x4*)(args.out + (size_t)m * DM) + 2 * lane;
; #pragma unroll
;             for (int jj = 0; jj < 4; ++jj) { const v4u z = __builtin_nontemporal_load(zr + 64 * jj); const f32x4 g0 = fg[128 * jj], g1 = fg[128 * jj + 1];
.LBB0_316:
	s_or_b64 exec, exec, s[2:3]
	s_andn2_b64 vcc, exec, s[86:87]
	s_barrier
	s_cbranch_vccnz .LBB0_321
	v_mbcnt_hi_u32_b32 v2, -1, v180
	v_and_b32_e32 v3, 64, v2
	v_add_u32_e32 v3, 64, v3
	v_xor_b32_e32 v4, 1, v2
	v_cmp_lt_i32_e32 vcc, v4, v3
	v_lshlrev_b32_e32 v10, 5, v173
	v_mov_b32_e32 v11, 0
	v_cndmask_b32_e32 v4, v2, v4, vcc
	v_lshlrev_b32_e32 v12, 2, v4
	v_xor_b32_e32 v4, 2, v2
	v_cmp_lt_i32_e32 vcc, v4, v3
	v_lshl_add_u64 v[0:1], s[28:29], 0, v[10:11]
	s_mov_b64 s[2:3], 0x1000
	v_cndmask_b32_e32 v4, v2, v4, vcc
	v_lshlrev_b32_e32 v13, 2, v4
	v_xor_b32_e32 v4, 4, v2
	v_cmp_lt_i32_e32 vcc, v4, v3
	s_ashr_i32 s57, s56, 31
	s_ashr_i32 s59, s58, 31
	v_cndmask_b32_e32 v4, v2, v4, vcc
	v_lshlrev_b32_e32 v14, 2, v4
	v_xor_b32_e32 v4, 8, v2
	v_cmp_lt_i32_e32 vcc, v4, v3
	s_lshl_b64 s[4:5], s[58:59], 12
	v_cmp_gt_u32_e64 s[0:1], 32, v173
	v_cndmask_b32_e32 v4, v2, v4, vcc
	v_lshlrev_b32_e32 v15, 2, v4
	v_xor_b32_e32 v4, 16, v2
	v_cmp_lt_i32_e32 vcc, v4, v3
	v_mov_b32_e32 v18, 0x358637bd
	s_mov_b32 s10, 0xf800000
	v_cndmask_b32_e32 v4, v2, v4, vcc
	v_lshlrev_b32_e32 v16, 2, v4
	v_xor_b32_e32 v4, 32, v2
	v_cmp_lt_i32_e32 vcc, v4, v3
	v_mov_b32_e32 v19, 0x260
	s_brev_b32 s11, 8
	v_cndmask_b32_e32 v2, v2, v4, vcc
	v_lshlrev_b32_e32 v17, 2, v2
	v_lshl_add_u64 v[2:3], v[0:1], 0, s[2:3]
	s_mov_b64 s[2:3], 0x1800
	v_lshl_add_u64 v[4:5], v[0:1], 0, s[2:3]
	s_lshl_b64 s[2:3], s[56:57], 12
	v_lshl_or_b32 v6, v173, 4, s2
	v_mov_b32_e32 v7, s3
	s_lshl_b64 s[2:3], s[56:57], 13
	s_add_u32 s2, s30, s2
	s_addc_u32 s3, s31, s3
	v_lshl_add_u64 v[8:9], s[2:3], 0, v[10:11]
	s_mov_b64 s[2:3], 0x1810
	v_lshl_add_u64 v[8:9], v[8:9], 0, s[2:3]
	s_lshl_b64 s[2:3], s[56:57], 7
	v_mov_b32_e32 v173, v11
	v_lshl_add_u64 v[10:11], s[2:3], 0, v[172:173]
	s_mov_b64 s[2:3], 0x2400000
	s_lshl_b64 s[6:7], s[58:59], 13
	v_lshl_add_u64 v[10:11], v[10:11], 0, s[2:3]
	s_lshl_b64 s[8:9], s[58:59], 7
	s_movk_i32 s12, 0xf000
	global_load_dwordx4 v[64:67], v[0:1], off
	global_load_dwordx4 v[68:71], v[0:1], off offset:16
	global_load_dwordx4 v[72:75], v[0:1], off offset:2048
	global_load_dwordx4 v[76:79], v[0:1], off offset:2064
	global_load_dwordx4 v[80:83], v[2:3], off
	global_load_dwordx4 v[84:87], v[2:3], off offset:16
	global_load_dwordx4 v[88:91], v[4:5], off
	global_load_dwordx4 v[92:95], v[4:5], off offset:16
	s_waitcnt vmcnt(0)
	s_branch .LBB0_319
; __global__ void __launch_bounds__(NWAVES * 64, 2) mixer_fwd(Args args) {
;     ...
;         for (int m = gw; m < MTOK; m += NGW) {
;             const float s = wave_sum(lane < 32 ? part[(size_t)m * 32 + lane] : 0.f);
;             const float r = 1.f / sqrtf(s * (1.f / DM) + 1e-6f);
;             const v4u* zr = (const v4u*)(zb + (size_t)m * DM) + lane; f32x4* orow = (f32x4*)(args.out + (size_t)m * DM) + 2 * lane;
; #pragma unroll
;             for (int jj = 0; jj < 4; ++jj) { const v4u z = __builtin_nontemporal_load(zr + 64 * jj); const f32x4 g0 = fg[128 * jj], g1 = fg[128 * jj + 1];
;                 const f32x4 a = {__uint_as_float(z.x << 16), __uint_as_float(z.x & 0xffff0000u), __uint_as_float(z.y << 16), __uint_as_float(z.y & 0xffff0000u)};
;                 const f32x4 b = {__uint_as_float(z.z << 16), __uint_as_float(z.z & 0xffff0000u), __uint_as_float(z.w << 16), __uint_as_float(z.w & 0xffff0000u)};
;                 __builtin_nontemporal_store(a * r * g0, orow + 128 * jj); __builtin_nontemporal_store(b * r * g1, orow + 128 * jj + 1); }
.LBB0_318:
	s_or_b64 exec, exec, s[2:3]
	v_lshl_add_u64 v[22:23], s[34:35], 0, v[6:7]
	v_add_co_u32_e32 v34, vcc, s11, v22
	s_waitcnt vmcnt(0)
	ds_bpermute_b32 v21, v12, v20
	v_addc_co_u32_e32 v35, vcc, 0, v23, vcc
	global_load_dwordx4 v[22:25], v[34:35], off nt
	global_load_dwordx4 v[44:47], v[34:35], off offset:1024 nt
	global_load_dwordx4 v[48:51], v[34:35], off offset:2048 nt
	global_load_dwordx4 v[52:55], v[34:35], off offset:3072 nt
	v_mov_b64_e32 v[26:27], v[64:65]
	v_mov_b64_e32 v[28:29], v[66:67]
	v_mov_b64_e32 v[30:31], v[68:69]
	v_mov_b64_e32 v[32:33], v[70:71]
	s_waitcnt lgkmcnt(0)
	v_add_f32_e32 v20, v20, v21
	ds_bpermute_b32 v21, v13, v20
	s_add_i32 s56, s56, s58
	v_lshl_add_u64 v[6:7], v[6:7], 0, s[4:5]
	s_cmp_gt_i32 s56, 0xffff
	v_lshl_add_u64 v[10:11], v[10:11], 0, s[8:9]
	s_waitcnt lgkmcnt(0)
	v_add_f32_e32 v20, v20, v21
	ds_bpermute_b32 v21, v14, v20
	s_waitcnt lgkmcnt(0)
	v_add_f32_e32 v20, v20, v21
	ds_bpermute_b32 v21, v15, v20
	s_waitcnt lgkmcnt(0)
	v_add_f32_e32 v20, v20, v21
	ds_bpermute_b32 v21, v16, v20
	s_waitcnt lgkmcnt(0)
	v_add_f32_e32 v20, v20, v21
	ds_bpermute_b32 v21, v17, v20
	s_waitcnt lgkmcnt(0)
	v_add_f32_e32 v20, v20, v21
	v_fmamk_f32 v20, v20, 0x3a000000, v18
	v_mul_f32_e32 v21, 0x4f800000, v20
	v_cmp_gt_f32_e32 vcc, s10, v20
	s_nop 1
	v_cndmask_b32_e32 v20, v20, v21, vcc
	v_sqrt_f32_e32 v21, v20
	s_nop 0
	v_add_u32_e32 v36, -1, v21
	v_add_u32_e32 v37, 1, v21
	v_fma_f32 v38, -v36, v21, v20
	v_fma_f32 v39, -v37, v21, v20
	v_cmp_ge_f32_e64 s[2:3], 0, v38
	s_nop 1
	v_cndmask_b32_e64 v21, v21, v36, s[2:3]
	v_cmp_lt_f32_e64 s[2:3], 0, v39
	s_nop 1
	v_cndmask_b32_e64 v21, v21, v37, s[2:3]
	v_mul_f32_e32 v36, 0x37800000, v21
	v_cndmask_b32_e32 v21, v21, v36, vcc
	v_cmp_class_f32_e32 vcc, v20, v19
	s_nop 1
	v_cndmask_b32_e32 v20, v21, v20, vcc
	v_div_scale_f32 v21, s[2:3], v20, v20, 1.0
	v_rcp_f32_e32 v38, v21
	v_add_co_u32_e32 v36, vcc, s12, v8
	v_fma_f32 v40, -v21, v38, 1.0
	s_nop 0
	v_addc_co_u32_e32 v37, vcc, -1, v9, vcc
	v_div_scale_f32 v39, vcc, 1.0, v20, 1.0
	v_fmac_f32_e32 v38, v40, v38
	v_mul_f32_e32 v40, v39, v38
	v_fma_f32 v41, -v21, v40, v39
	v_fmac_f32_e32 v40, v41, v38
	v_fma_f32 v21, -v21, v40, v39
	v_div_fmas_f32 v21, v21, v38, v40
	v_div_fixup_f32 v38, v21, v20, 1.0
	s_waitcnt vmcnt(0)
	v_lshlrev_b32_e32 v20, 16, v22
	v_and_b32_e32 v21, 0xffff0000, v22
	v_lshlrev_b32_e32 v22, 16, v23
	v_and_b32_e32 v23, 0xffff0000, v23
	v_lshlrev_b32_e32 v40, 16, v24
	v_and_b32_e32 v41, 0xffff0000, v24
	v_lshlrev_b32_e32 v24, 16, v25
	v_and_b32_e32 v25, 0xffff0000, v25
	v_pk_mul_f32 v[20:21], v[38:39], v[20:21] op_sel_hi:[0,1]
	v_pk_mul_f32 v[22:23], v[38:39], v[22:23] op_sel_hi:[0,1]
	v_pk_mul_f32 v[40:41], v[38:39], v[40:41] op_sel_hi:[0,1]
	v_pk_mul_f32 v[24:25], v[38:39], v[24:25] op_sel_hi:[0,1]
	v_pk_mul_f32 v[22:23], v[28:29], v[22:23]
	v_pk_mul_f32 v[20:21], v[26:27], v[20:21]
	v_pk_mul_f32 v[26:27], v[32:33], v[24:25]
	v_pk_mul_f32 v[24:25], v[30:31], v[40:41]
	global_store_dwordx4 v[36:37], v[20:23], off offset:-2064 nt
	global_store_dwordx4 v[36:37], v[24:27], off offset:-2048 nt
	s_nop 1
	v_mov_b64_e32 v[20:21], v[44:45]
	v_mov_b64_e32 v[22:23], v[46:47]
	v_mov_b64_e32 v[24:25], v[72:73]
	v_mov_b64_e32 v[26:27], v[74:75]
	v_mov_b64_e32 v[28:29], v[76:77]
	v_mov_b64_e32 v[30:31], v[78:79]
	v_lshlrev_b32_e32 v32, 16, v20
	v_and_b32_e32 v33, 0xffff0000, v20
	v_lshlrev_b32_e32 v20, 16, v21
	v_and_b32_e32 v21, 0xffff0000, v21
	v_lshlrev_b32_e32 v40, 16, v22
	v_and_b32_e32 v41, 0xffff0000, v22
	v_lshlrev_b32_e32 v22, 16, v23
	v_and_b32_e32 v23, 0xffff0000, v23
	v_pk_mul_f32 v[32:33], v[38:39], v[32:33] op_sel_hi:[0,1]
	v_pk_mul_f32 v[20:21], v[38:39], v[20:21] op_sel_hi:[0,1]
	v_pk_mul_f32 v[40:41], v[38:39], v[40:41] op_sel_hi:[0,1]
	v_pk_mul_f32 v[42:43], v[38:39], v[22:23] op_sel_hi:[0,1]
	v_pk_mul_f32 v[22:23], v[26:27], v[20:21]
	v_pk_mul_f32 v[20:21], v[24:25], v[32:33]
	v_pk_mul_f32 v[26:27], v[30:31], v[42:43]
	v_pk_mul_f32 v[24:25], v[28:29], v[40:41]
	global_store_dwordx4 v[36:37], v[20:23], off offset:-16 nt
	global_store_dwordx4 v[8:9], v[24:27], off offset:-4096 nt
	s_nop 1
	v_mov_b64_e32 v[20:21], v[48:49]
	v_mov_b64_e32 v[22:23], v[50:51]
	v_mov_b64_e32 v[24:25], v[80:81]
	v_mov_b64_e32 v[26:27], v[82:83]
	v_mov_b64_e32 v[28:29], v[84:85]
	v_mov_b64_e32 v[30:31], v[86:87]
	v_lshlrev_b32_e32 v32, 16, v20
	v_and_b32_e32 v33, 0xffff0000, v20
	v_lshlrev_b32_e32 v20, 16, v21
	v_and_b32_e32 v21, 0xffff0000, v21
	v_lshlrev_b32_e32 v36, 16, v22
	v_and_b32_e32 v37, 0xffff0000, v22
	v_lshlrev_b32_e32 v22, 16, v23
	v_and_b32_e32 v23, 0xffff0000, v23
	v_pk_mul_f32 v[32:33], v[38:39], v[32:33] op_sel_hi:[0,1]
	v_pk_mul_f32 v[20:21], v[38:39], v[20:21] op_sel_hi:[0,1]
	v_pk_mul_f32 v[36:37], v[38:39], v[36:37] op_sel_hi:[0,1]
	v_pk_mul_f32 v[40:41], v[38:39], v[22:23] op_sel_hi:[0,1]
	v_pk_mul_f32 v[22:23], v[26:27], v[20:21]
	v_pk_mul_f32 v[20:21], v[24:25], v[32:33]
	v_pk_mul_f32 v[26:27], v[30:31], v[40:41]
	v_pk_mul_f32 v[24:25], v[28:29], v[36:37]
	global_store_dwordx4 v[8:9], v[20:23], off offset:-2064 nt
	global_store_dwordx4 v[8:9], v[24:27], off offset:-2048 nt
	s_nop 1
	v_mov_b64_e32 v[20:21], v[52:53]
	v_mov_b64_e32 v[22:23], v[54:55]
	v_mov_b64_e32 v[24:25], v[88:89]
	v_mov_b64_e32 v[26:27], v[90:91]
	v_mov_b64_e32 v[28:29], v[92:93]
	v_mov_b64_e32 v[30:31], v[94:95]
	v_lshlrev_b32_e32 v32, 16, v20
	v_and_b32_e32 v33, 0xffff0000, v20
	v_lshlrev_b32_e32 v20, 16, v21
	v_and_b32_e32 v21, 0xffff0000, v21
	v_lshlrev_b32_e32 v34, 16, v22
	v_and_b32_e32 v35, 0xffff0000, v22
	v_lshlrev_b32_e32 v22, 16, v23
	v_and_b32_e32 v23, 0xffff0000, v23
	v_pk_mul_f32 v[32:33], v[38:39], v[32:33] op_sel_hi:[0,1]
	v_pk_mul_f32 v[20:21], v[38:39], v[20:21] op_sel_hi:[0,1]
	v_pk_mul_f32 v[34:35], v[38:39], v[34:35] op_sel_hi:[0,1]
	v_pk_mul_f32 v[36:37], v[38:39], v[22:23] op_sel_hi:[0,1]
	v_pk_mul_f32 v[22:23], v[26:27], v[20:21]
	v_pk_mul_f32 v[20:21], v[24:25], v[32:33]
	v_pk_mul_f32 v[26:27], v[30:31], v[36:37]
	v_pk_mul_f32 v[24:25], v[28:29], v[34:35]
	global_store_dwordx4 v[8:9], v[20:23], off offset:-16 nt
	global_store_dwordx4 v[8:9], v[24:27], off nt
	v_lshl_add_u64 v[8:9], v[8:9], 0, s[6:7]
	s_cbranch_scc1 .LBB0_321
